# NA loop: skip the PV MFMAs and V reads of the 16-key step whose probabilities are structurally zero for the wave's query block
# baseline (speedup 1.0000x reference)
; DI void attn_na_unit(const Params& p, int li, int b, int r, int hp, char* smem) {
;     ...
;   const int qbk = w & 1, hs = w >> 1, head = 2 * hp + hs;
;   const int wq = 32 * qbk + r32;
;   const int qrow = b * S_ + r * 64 + wq;
;   int cs = wq - 8; cs = cs < 0 ? 0 : (cs > 48 ? 48 : cs);
;   int rs = r - 4; rs = rs < 0 ? 0 : (rs > 56 ? 56 : rs);
;     ...
;     const int drow = rs + kt - r + 7;
;     const float* trow = tab + hs * 465 + drow * 31;
; #pragma unroll
;     for (int i = 0; i < 16; ++i) {
;       const int kc0 = (i & 3) + 8 * (i >> 2) + 4 * hh;
;       const int kc1 = kc0 + 32;
;       const bool v0 = (unsigned)(kc0 - cs) < 16u;
;       const bool v1 = (unsigned)(kc1 - cs) < 16u;
;       const int d0 = v0 ? (kc0 - wq + 15) : 0;
;       const int d1 = v1 ? (kc1 - wq + 15) : 0;
;       const float b0 = trow[d0], b1 = trow[d1];
;       s0[i] = v0 ? s0[i] + b0 : -1e30f;
;       s1[i] = v1 ? s1[i] + b1 : -1e30f;
;     }
.LBB0_1537:
	v_lshlrev_b32_e32 v126, 6, v39
	v_mul_u32_u24_e32 v39, 0x110, v33
	v_mul_u32_u24_e32 v42, 0x140, v33
	v_add_f32_e32 v33, 0, v50
	v_add_f32_e32 v50, 0, v60
	v_mul_f32_e32 v34, v50, v34
	v_add_f32_e32 v60, v33, v61
	v_cndmask_b32_e64 v128, v60, v33, s[6:7]
	v_cndmask_b32_e64 v127, v34, v50, s[6:7]
	s_movk_i32 s6, 0x7c
	v_mad_u32_u24 v34, v38, s6, v41
	v_add_u32_e32 v32, v34, v32
	v_lshlrev_b32_e32 v37, 2, v37
	v_mul_lo_u32 v36, v36, s6
	v_sub_u32_e32 v32, v32, v37
	v_lshlrev_b32_e32 v37, 1, v35
	v_sub_u32_e32 v32, v32, v36
	v_and_b32_e32 v37, 0x80, v37
	v_sub_u32_e32 v32, v32, v37
	v_add_u32_e32 v130, v120, v32
	v_lshl_add_u32 v32, v44, 2, v34
	v_sub_u32_e32 v32, v32, v36
	v_add_u32_e32 v131, v119, v32
	v_lshl_add_u32 v32, v45, 2, v34
	v_sub_u32_e32 v32, v32, v36
	v_add_u32_e32 v132, v119, v32
	v_lshl_add_u32 v32, v46, 2, v34
	v_sub_u32_e32 v32, v32, v36
	v_add_u32_e32 v133, v119, v32
	v_lshl_add_u32 v32, v47, 2, v34
	v_sub_u32_e32 v32, v32, v36
	v_add_u32_e32 v134, v119, v32
	v_lshl_add_u32 v32, v48, 2, v34
	v_sub_u32_e32 v32, v32, v36
	v_add_u32_e32 v135, v119, v32
	v_lshl_add_u32 v32, v49, 2, v34
	v_sub_u32_e32 v32, v32, v36
	v_add_u32_e32 v136, v119, v32
	v_lshl_add_u32 v32, v51, 2, v34
	v_sub_u32_e32 v32, v32, v36
	v_add_u32_e32 v137, v119, v32
	v_lshl_add_u32 v32, v52, 2, v34
	v_sub_u32_e32 v32, v32, v36
	v_add_u32_e32 v138, v119, v32
	v_lshl_add_u32 v32, v53, 2, v34
	v_sub_u32_e32 v32, v32, v36
	v_add_u32_e32 v139, v119, v32
	v_lshl_add_u32 v32, v54, 2, v34
	v_sub_u32_e32 v32, v32, v36
	v_add_u32_e32 v140, v119, v32
	v_lshl_add_u32 v32, v55, 2, v34
	v_sub_u32_e32 v32, v32, v36
	v_add_u32_e32 v141, v119, v32
	v_lshl_add_u32 v32, v56, 2, v34
	v_sub_u32_e32 v32, v32, v36
	v_add_u32_e32 v142, v119, v32
	v_lshl_add_u32 v32, v57, 2, v34
	v_sub_u32_e32 v32, v32, v36
	v_add_u32_e32 v143, v119, v32
	v_lshl_add_u32 v32, v58, 2, v34
	v_sub_u32_e32 v32, v32, v36
	v_add_u32_e32 v146, v119, v32
	v_lshl_add_u32 v32, v59, 2, v34
	v_sub_u32_e32 v32, v32, v36
	v_add_u32_e32 v147, v119, v32
	v_and_b32_e32 v32, 15, v35
	v_and_b32_e32 v33, 3, v121
	v_lshlrev_b32_e32 v32, 4, v32
	v_lshlrev_b64 v[62:63], 9, v[144:145]
	v_lshl_add_u32 v38, v43, 2, v34
	v_lshl_or_b32 v144, v33, 8, v32
	v_sub_u32_e32 v38, v38, v36
	v_lshl_add_u64 v[32:33], v[62:63], 1, v[144:145]
	v_add_u32_e32 v129, v119, v38
	v_lshl_add_u64 v[114:115], s[34:35], 0, v[32:33]
	s_movk_i32 s9, 0xfc9c
	v_add_u32_e32 v144, v40, v39
	v_add_u32_e32 v148, v40, v42
	v_readfirstlane_b32 s100, v182
	s_branch .LBB0_1539

; DI f32x16 mfma32(bf16x8 a, bf16x8 b, f32x16 c) { return __builtin_amdgcn_mfma_f32_32x32x16_bf16(a, b, c, 0, 0, 0); }
; DI bool softmax_tile(f32x16& s0, f32x16& s1, float& m, float& l, float& alpha, bf16x8* pf, int lane, bool first, bool check) {
;     ...
;   float sum = 0.f;
; #pragma unroll
;   for (int i = 0; i < 16; ++i) { s0[i] = __builtin_amdgcn_exp2f(s0[i]); sum += s0[i]; }
; #pragma unroll
;   for (int i = 0; i < 16; ++i) { s1[i] = __builtin_amdgcn_exp2f(s1[i]); sum += s1[i]; }
;   l += sum;
;   pf[0] = pack8(s0, 0); pf[1] = pack8(s0, 8); pf[2] = pack8(s1, 0); pf[3] = pack8(s1, 8);
;   alpha = 1.f;
;   if (!check) return false;
;   const float rsum = sum + shx(sum, 32, lane);
;   const bool trig = rsum > 65536.f;
;   const bool resc = (__builtin_amdgcn_ballot_w64(trig) != 0ull);
;   alpha = 1.f;
;   if (resc) {
;     const float d = trig ? (float)(__builtin_amdgcn_frexp_expf(rsum) - 7) : 0.f;
;     alpha = __builtin_amdgcn_exp2f(-d);
;     m += d; l *= alpha;
;   }
; DI void attn_na_unit(const Params& p, int li, int b, int r, int hp, char* smem) {
;     ...
;     float alpha; bf16x8 pf[4];
;     const bool resc = softmax_tile(s0, s1, m, l, alpha, pf, lane, kt == 0, true);
;     {
;       bf16x8 vf[8];
; #pragma unroll
;       for (int s = 0; s < 4; ++s) { vf[2 * s] = ld_vfrag_tr(vs, vbase, VR, 16 * s, hs * 64); vf[2 * s + 1] = ld_vfrag_tr(vs, vbase, VR, 16 * s, hs * 64 + 32); }
;       __builtin_amdgcn_sched_barrier(0); __builtin_amdgcn_s_setprio(1);
; #pragma unroll
;       for (int s = 0; s < 4; ++s) { O0 = mfma32(vf[2 * s], pf[s], O0); O1 = mfma32(vf[2 * s + 1], pf[s], O1); }
;     __builtin_amdgcn_s_setprio(0);
; }
;     if (resc) { scale16(O0, alpha); scale16(O1, alpha); }
.LBB0_1573:
	s_or_b64 exec, exec, s[6:7]
	s_waitcnt lgkmcnt(0)
	v_add_f32_e32 v47, v47, v62
	v_exp_f32_e32 v62, v151
	v_exp_f32_e32 v149, v149
	v_exp_f32_e32 v49, v49
	v_exp_f32_e32 v48, v48
	v_add_f32_e32 v63, 0, v62
	v_exp_f32_e32 v51, v51
	v_add_f32_e32 v63, v63, v149
	v_exp_f32_e32 v50, v50
	v_add_f32_e32 v63, v63, v49
	v_exp_f32_e32 v53, v53
	v_add_f32_e32 v63, v63, v48
	v_exp_f32_e32 v52, v52
	v_add_f32_e32 v63, v63, v51
	v_exp_f32_e32 v55, v55
	v_add_f32_e32 v63, v63, v50
	v_exp_f32_e32 v54, v54
	v_add_f32_e32 v63, v63, v53
	v_exp_f32_e32 v57, v57
	v_add_f32_e32 v63, v63, v52
	v_exp_f32_e32 v56, v56
	v_add_f32_e32 v63, v63, v55
	v_exp_f32_e32 v59, v59
	v_add_f32_e32 v63, v63, v54
	v_exp_f32_e32 v58, v58
	v_add_f32_e32 v32, v32, v150
	v_add_f32_e32 v63, v63, v57
	v_exp_f32_e32 v61, v61
	v_add_f32_e32 v33, v33, v152
	v_cndmask_b32_e64 v32, v195, v32, s[78:79]
	v_add_f32_e32 v63, v63, v56
	v_exp_f32_e32 v60, v60
	v_cndmask_b32_e64 v33, v195, v33, s[92:93]
	v_add_f32_e32 v63, v63, v59
	v_exp_f32_e32 v32, v32
	v_add_f32_e32 v34, v34, v153
	v_add_f32_e32 v63, v63, v58
	v_exp_f32_e32 v150, v33
	v_add_f32_e32 v35, v35, v155
	v_cndmask_b32_e64 v34, v195, v34, s[94:95]
	v_add_f32_e32 v63, v63, v61
	v_add_f32_e32 v36, v36, v156
	v_cndmask_b32_e64 v35, v195, v35, s[72:73]
	v_add_f32_e32 v63, v63, v60
	v_exp_f32_e32 v34, v34
	v_add_f32_e32 v37, v37, v157
	v_cndmask_b32_e64 v36, v195, v36, s[80:81]
	v_add_f32_e32 v63, v32, v63
	v_exp_f32_e32 v35, v35
	v_add_f32_e32 v38, v38, v158
	v_cndmask_b32_e64 v37, v195, v37, s[74:75]
	v_add_f32_e32 v33, v150, v63
	v_exp_f32_e32 v63, v36
	v_add_f32_e32 v39, v39, v159
	v_cndmask_b32_e64 v38, v195, v38, s[58:59]
	v_exp_f32_e32 v151, v37
	v_add_f32_e32 v40, v40, v160
	v_cndmask_b32_e64 v39, v195, v39, s[48:49]
	v_add_f32_e32 v33, v34, v33
	v_exp_f32_e32 v152, v38
	v_add_f32_e32 v41, v41, v161
	v_cndmask_b32_e64 v40, v195, v40, s[50:51]
	v_add_f32_e32 v33, v35, v33
	v_exp_f32_e32 v153, v39
	v_add_f32_e32 v42, v42, v162
	v_cndmask_b32_e64 v41, v195, v41, s[62:63]
	v_add_f32_e32 v33, v63, v33
	v_exp_f32_e32 v154, v40
	v_add_f32_e32 v43, v43, v163
	v_cndmask_b32_e64 v42, v195, v42, s[38:39]
	v_add_f32_e32 v33, v151, v33
	v_exp_f32_e32 v155, v41
	v_add_f32_e32 v44, v44, v164
	v_cndmask_b32_e64 v43, v195, v43, s[44:45]
	v_add_f32_e32 v33, v152, v33
	v_exp_f32_e32 v156, v42
	v_add_f32_e32 v45, v45, v165
	v_cndmask_b32_e64 v44, v195, v44, s[56:57]
	v_add_f32_e32 v33, v153, v33
	v_exp_f32_e32 v157, v43
	v_add_f32_e32 v46, v46, v166
	v_cndmask_b32_e64 v45, v195, v45, s[82:83]
	v_add_f32_e32 v33, v154, v33
	v_exp_f32_e32 v158, v44
	v_cndmask_b32_e64 v46, v195, v46, s[84:85]
	v_add_f32_e32 v33, v155, v33
	v_exp_f32_e32 v159, v45
	v_cndmask_b32_e64 v47, v195, v47, s[2:3]
	v_add_f32_e32 v33, v156, v33
	v_exp_f32_e32 v160, v46
	v_add_f32_e32 v33, v157, v33
	v_exp_f32_e32 v161, v47
	v_add_f32_e32 v33, v158, v33
	v_add_f32_e32 v33, v159, v33
	v_add_f32_e32 v33, v160, v33
	v_add_f32_e32 v33, v161, v33
	v_cvt_pk_bf16_f32 v36, v62, v149
	v_cvt_pk_bf16_f32 v37, v49, v48
	v_cvt_pk_bf16_f32 v38, v51, v50
	v_cvt_pk_bf16_f32 v39, v53, v52
	v_cvt_pk_bf16_f32 v40, v55, v54
	v_cvt_pk_bf16_f32 v41, v57, v56
	v_cvt_pk_bf16_f32 v42, v59, v58
	v_cvt_pk_bf16_f32 v43, v61, v60
	v_cvt_pk_bf16_f32 v44, v32, v150
	v_cvt_pk_bf16_f32 v46, v63, v151
	v_cvt_pk_bf16_f32 v47, v152, v153
	v_cvt_pk_bf16_f32 v48, v154, v155
	v_cvt_pk_bf16_f32 v49, v156, v157
	v_cvt_pk_bf16_f32 v50, v158, v159
	v_cvt_pk_bf16_f32 v51, v160, v161
	s_bitcmp1_b32 s100, 6
	s_cbranch_scc1 .Lna_rd_q1
	ds_read_b64_tr_b16 v[52:53], v125 offset:17408
	ds_read_b64_tr_b16 v[54:55], v125 offset:19968
	ds_read_b64_tr_b16 v[56:57], v125 offset:17472
	ds_read_b64_tr_b16 v[58:59], v125 offset:20032
.Lna_rd_q1:
	ds_read_b64_tr_b16 v[60:61], v125 offset:22528
	ds_read_b64_tr_b16 v[62:63], v125 offset:25088
	ds_read_b64_tr_b16 v[150:151], v125 offset:22592
	ds_read_b64_tr_b16 v[152:153], v125 offset:25152
	ds_read_b64_tr_b16 v[154:155], v125 offset:27648
	ds_read_b64_tr_b16 v[156:157], v125 offset:30208
	ds_read_b64_tr_b16 v[158:159], v125 offset:27712
	ds_read_b64_tr_b16 v[160:161], v125 offset:30272
	s_cbranch_scc0 .Lna_rd_q0
	ds_read_b64_tr_b16 v[162:163], v125 offset:32768
	ds_read_b64_tr_b16 v[164:165], v125 offset:35328
	ds_read_b64_tr_b16 v[166:167], v125 offset:32832
	ds_read_b64_tr_b16 v[168:169], v125 offset:35392
.Lna_rd_q0:
	ds_bpermute_b32 v32, v124, v33
	v_cvt_pk_bf16_f32 v45, v34, v35
	s_waitcnt lgkmcnt(0)
	v_add_f32_e32 v32, v33, v32
	v_cmp_lt_f32_e32 vcc, s88, v32
	v_frexp_exp_i32_f32_e32 v32, v32
	v_add_u32_e32 v32, -7, v32
	v_cvt_f32_i32_e32 v32, v32
	s_cmp_eq_u64 vcc, 0
	s_cselect_b64 s[6:7], -1, 0
	v_cndmask_b32_e32 v34, 0, v32, vcc
	v_exp_f32_e64 v32, -v34
	s_setprio 1
	s_bitcmp1_b32 s100, 6
	s_cbranch_scc1 .Lna_mm_q1
	v_mfma_f32_32x32x16_bf16 v[16:31], v[52:55], v[36:39], v[16:31]
	v_mfma_f32_32x32x16_bf16 v[0:15], v[56:59], v[36:39], v[0:15]
.Lna_mm_q1:
	v_mfma_f32_32x32x16_bf16 v[16:31], v[60:63], v[40:43], v[16:31]
	v_mfma_f32_32x32x16_bf16 v[0:15], v[150:153], v[40:43], v[0:15]
	v_mfma_f32_32x32x16_bf16 v[16:31], v[154:157], v[44:47], v[16:31]
	v_mfma_f32_32x32x16_bf16 v[0:15], v[158:161], v[44:47], v[0:15]
	s_cbranch_scc0 .Lna_mm_q0
	v_mfma_f32_32x32x16_bf16 v[16:31], v[162:165], v[48:51], v[16:31]
	v_mfma_f32_32x32x16_bf16 v[0:15], v[166:169], v[48:51], v[0:15]
.Lna_mm_q0:
	s_setprio 0
	s_cbranch_vccz .LBB0_1538
	s_nop 8
	v_pk_mul_f32 v[30:31], v[32:33], v[30:31] op_sel_hi:[0,1]
	v_pk_mul_f32 v[28:29], v[32:33], v[28:29] op_sel_hi:[0,1]
	v_pk_mul_f32 v[26:27], v[32:33], v[26:27] op_sel_hi:[0,1]
	v_pk_mul_f32 v[24:25], v[32:33], v[24:25] op_sel_hi:[0,1]
	v_pk_mul_f32 v[22:23], v[32:33], v[22:23] op_sel_hi:[0,1]
	v_pk_mul_f32 v[20:21], v[32:33], v[20:21] op_sel_hi:[0,1]
	v_pk_mul_f32 v[18:19], v[32:33], v[18:19] op_sel_hi:[0,1]
	v_pk_mul_f32 v[16:17], v[32:33], v[16:17] op_sel_hi:[0,1]
	v_pk_mul_f32 v[14:15], v[32:33], v[14:15] op_sel_hi:[0,1]
	v_pk_mul_f32 v[12:13], v[32:33], v[12:13] op_sel_hi:[0,1]
	v_pk_mul_f32 v[10:11], v[32:33], v[10:11] op_sel_hi:[0,1]
	v_pk_mul_f32 v[8:9], v[32:33], v[8:9] op_sel_hi:[0,1]
	v_pk_mul_f32 v[6:7], v[32:33], v[6:7] op_sel_hi:[0,1]
	v_pk_mul_f32 v[4:5], v[32:33], v[4:5] op_sel_hi:[0,1]
	v_pk_mul_f32 v[2:3], v[32:33], v[2:3] op_sel_hi:[0,1]
	v_pk_mul_f32 v[0:1], v[32:33], v[0:1] op_sel_hi:[0,1]
	s_branch .LBB0_1538
